# diff attention loop: P.V MFMAs interleaved with next key-group exp/pack/rowsum VALU; scalar subs instead of pk_add; dedicated V fragment registers
# speedup vs baseline: 1.0001x; 1.0001x over previous
.LBB0_483:
	v_sub_f32_e32 v0, v150, v0
	v_add3_u32 v203, s5, v133, v130
	ds_read_b128 v[224:227], v203 offset:17408
	ds_read_b128 v[228:231], v203 offset:22016
	ds_read_b128 v[232:235], v203 offset:26624
	ds_read_b128 v[236:239], v203 offset:31232
	ds_read_b128 v[240:243], v203 offset:17440
	ds_read_b128 v[244:247], v203 offset:22048
	ds_read_b128 v[248:251], v203 offset:26656
	ds_read_b128 v[204:207], v203 offset:31264
	v_sub_f32_e32 v82, v82, v0
	v_sub_f32_e32 v83, v83, v0
	v_sub_f32_e32 v84, v84, v0
	v_sub_f32_e32 v85, v85, v0
	v_exp_f32_e32 v82, v82
	v_exp_f32_e32 v83, v83
	v_sub_f32_e32 v86, v86, v0
	v_sub_f32_e32 v87, v87, v0
	v_sub_f32_e32 v88, v88, v0
	v_sub_f32_e32 v89, v89, v0
	v_exp_f32_e32 v84, v84
	v_exp_f32_e32 v85, v85
	v_exp_f32_e32 v86, v86
	v_exp_f32_e32 v87, v87
	v_exp_f32_e32 v88, v88
	v_exp_f32_e32 v89, v89
	v_cvt_pk_bf16_f32 v170, v82, v83
	v_cvt_pk_bf16_f32 v171, v84, v85
	v_cvt_pk_bf16_f32 v172, v86, v87
	v_cvt_pk_bf16_f32 v173, v88, v89
	v_add_f32_e32 v186, v82, v83
	v_add_f32_e32 v187, v84, v85
	v_add_f32_e32 v186, v186, v86
	v_add_f32_e32 v187, v187, v87
	v_add_f32_e32 v186, v186, v88
	v_add_f32_e32 v187, v187, v89
	s_setprio 1
	s_waitcnt lgkmcnt(4)
	v_mfma_f32_32x32x16_bf16 v[50:65], v[224:227], v[170:173], v[50:65]
	v_sub_f32_e32 v90, v90, v0
	v_sub_f32_e32 v91, v91, v0
	v_sub_f32_e32 v92, v92, v0
	v_sub_f32_e32 v93, v93, v0
	v_exp_f32_e32 v90, v90
	v_exp_f32_e32 v91, v91
	v_mfma_f32_32x32x16_bf16 v[34:49], v[228:231], v[170:173], v[34:49]
	v_sub_f32_e32 v94, v94, v0
	v_sub_f32_e32 v95, v95, v0
	v_sub_f32_e32 v96, v96, v0
	v_sub_f32_e32 v97, v97, v0
	v_exp_f32_e32 v92, v92
	v_exp_f32_e32 v93, v93
	v_mfma_f32_32x32x16_bf16 v[18:33], v[232:235], v[170:173], v[18:33]
	v_exp_f32_e32 v94, v94
	v_exp_f32_e32 v95, v95
	v_exp_f32_e32 v96, v96
	v_exp_f32_e32 v97, v97
	v_cvt_pk_bf16_f32 v174, v90, v91
	v_cvt_pk_bf16_f32 v175, v92, v93
	v_mfma_f32_32x32x16_bf16 v[2:17], v[236:239], v[170:173], v[2:17]
	ds_read_b128 v[224:227], v203 offset:17472
	ds_read_b128 v[228:231], v203 offset:22080
	ds_read_b128 v[232:235], v203 offset:26688
	ds_read_b128 v[236:239], v203 offset:31296
	v_cvt_pk_bf16_f32 v176, v94, v95
	v_cvt_pk_bf16_f32 v177, v96, v97
	v_add_f32_e32 v186, v186, v90
	v_add_f32_e32 v187, v187, v91
	v_add_f32_e32 v186, v186, v92
	v_add_f32_e32 v187, v187, v93
	v_add_f32_e32 v186, v186, v94
	v_add_f32_e32 v187, v187, v95
	v_add_f32_e32 v186, v186, v96
	v_add_f32_e32 v187, v187, v97
	s_waitcnt lgkmcnt(4)
	v_mfma_f32_32x32x16_bf16 v[50:65], v[240:243], v[174:177], v[50:65]
	v_sub_f32_e32 v66, v66, v0
	v_sub_f32_e32 v67, v67, v0
	v_sub_f32_e32 v68, v68, v0
	v_sub_f32_e32 v69, v69, v0
	v_exp_f32_e32 v66, v66
	v_exp_f32_e32 v67, v67
	v_mfma_f32_32x32x16_bf16 v[34:49], v[244:247], v[174:177], v[34:49]
	v_sub_f32_e32 v70, v70, v0
	v_sub_f32_e32 v71, v71, v0
	v_sub_f32_e32 v72, v72, v0
	v_sub_f32_e32 v73, v73, v0
	v_exp_f32_e32 v68, v68
	v_exp_f32_e32 v69, v69
	v_mfma_f32_32x32x16_bf16 v[18:33], v[248:251], v[174:177], v[18:33]
	v_exp_f32_e32 v70, v70
	v_exp_f32_e32 v71, v71
	v_exp_f32_e32 v72, v72
	v_exp_f32_e32 v73, v73
	v_cvt_pk_bf16_f32 v178, v66, v67
	v_cvt_pk_bf16_f32 v179, v68, v69
	v_mfma_f32_32x32x16_bf16 v[2:17], v[204:207], v[174:177], v[2:17]
	ds_read_b128 v[240:243], v203 offset:17504
	ds_read_b128 v[244:247], v203 offset:22112
	ds_read_b128 v[248:251], v203 offset:26720
	ds_read_b128 v[204:207], v203 offset:31328
	v_cvt_pk_bf16_f32 v180, v70, v71
	v_cvt_pk_bf16_f32 v181, v72, v73
	v_add_f32_e32 v186, v186, v66
	v_add_f32_e32 v187, v187, v67
	v_add_f32_e32 v186, v186, v68
	v_add_f32_e32 v187, v187, v69
	v_add_f32_e32 v186, v186, v70
	v_add_f32_e32 v187, v187, v71
	v_add_f32_e32 v186, v186, v72
	v_add_f32_e32 v187, v187, v73
	s_waitcnt lgkmcnt(4)
	v_mfma_f32_32x32x16_bf16 v[50:65], v[224:227], v[178:181], v[50:65]
	v_sub_f32_e32 v74, v74, v0
	v_sub_f32_e32 v75, v75, v0
	v_sub_f32_e32 v76, v76, v0
	v_sub_f32_e32 v77, v77, v0
	v_exp_f32_e32 v74, v74
	v_exp_f32_e32 v75, v75
	v_mfma_f32_32x32x16_bf16 v[34:49], v[228:231], v[178:181], v[34:49]
	v_sub_f32_e32 v78, v78, v0
	v_sub_f32_e32 v79, v79, v0
	v_sub_f32_e32 v80, v80, v0
	v_sub_f32_e32 v81, v81, v0
	v_exp_f32_e32 v76, v76
	v_exp_f32_e32 v77, v77
	v_mfma_f32_32x32x16_bf16 v[18:33], v[232:235], v[178:181], v[18:33]
	v_exp_f32_e32 v78, v78
	v_exp_f32_e32 v79, v79
	v_exp_f32_e32 v80, v80
	v_exp_f32_e32 v81, v81
	v_cvt_pk_bf16_f32 v182, v74, v75
	v_cvt_pk_bf16_f32 v183, v76, v77
	v_mfma_f32_32x32x16_bf16 v[2:17], v[236:239], v[178:181], v[2:17]
	v_cvt_pk_bf16_f32 v184, v78, v79
	v_cvt_pk_bf16_f32 v185, v80, v81
	v_add_f32_e32 v186, v186, v74
	v_add_f32_e32 v187, v187, v75
	v_add_f32_e32 v186, v186, v76
	v_add_f32_e32 v187, v187, v77
	v_add_f32_e32 v186, v186, v78
	v_add_f32_e32 v187, v187, v79
	v_add_f32_e32 v186, v186, v80
	v_add_f32_e32 v187, v187, v81
	s_waitcnt lgkmcnt(0)
	v_mfma_f32_32x32x16_bf16 v[50:65], v[240:243], v[182:185], v[50:65]
	v_mfma_f32_32x32x16_bf16 v[34:49], v[244:247], v[182:185], v[34:49]
	v_mfma_f32_32x32x16_bf16 v[18:33], v[248:251], v[182:185], v[18:33]
	v_mfma_f32_32x32x16_bf16 v[2:17], v[204:207], v[182:185], v[2:17]
	s_setprio 0
	v_add_f32_e32 v186, v186, v187
	v_add_f32_e32 v131, v131, v186
	s_or_b64 exec, exec, s[64:65]
	s_andn2_b64 vcc, exec, s[62:63]
	s_cbranch_vccnz .LBB0_474
